# UP0/UP1/QKV unit boundaries: next unit row-scale loads issued right after the K-loop into dead fragment registers instead of after the epilogue
# speedup vs baseline: 1.0032x; 1.0032x over previous
.LBB0_858:
	ds_read_b128 v[164:167], v173
	ds_read_b128 v[180:183], v173 offset:1024
	ds_read_b128 v[184:187], v173 offset:2048
	ds_read_b128 v[188:191], v173 offset:3072
	ds_read_b128 v[192:195], v174
	ds_read_b128 v[196:199], v174 offset:1024
	ds_read_b128 v[200:203], v174 offset:2048
	ds_read_b128 v[204:207], v174 offset:3072
	s_add_u32 s38, s36, 0xfffc0080
	s_addc_u32 s39, s37, -1
	s_cmp_eq_u32 s61, 12
	s_cselect_b32 s41, s25, s39
	s_cselect_b32 s40, s31, s38
	s_cselect_b32 s39, s23, s60
	s_cselect_b32 s38, s58, s59
	v_lshl_add_u64 v[176:177], s[36:37], 0, v[142:143]
	s_add_i32 m0, s35, 0xc000
	ds_read_b128 v[208:211], v175
	ds_read_b128 v[212:215], v175 offset:1024
	ds_read_b128 v[216:219], v175 offset:2048
	ds_read_b128 v[220:223], v175 offset:3072
	ds_read_b128 v[224:227], v175 offset:4096
	ds_read_b128 v[228:231], v175 offset:5120
	ds_read_b128 v[232:235], v175 offset:6144
	ds_read_b128 v[236:239], v175 offset:7168
	global_load_lds_dwordx4 v[176:177], off
	v_lshl_add_u64 v[176:177], s[36:37], 0, v[140:141]
	s_add_i32 m0, s35, 0xe000
	s_nop 0
	global_load_lds_dwordx4 v[176:177], off
	s_waitcnt vmcnt(8)
	s_waitcnt lgkmcnt(0)
	s_barrier
	s_setprio 1
	s_waitcnt lgkmcnt(0)
	v_mfma_f32_16x16x32_bf16 v[126:129], v[164:167], v[208:211], v[126:129]
	v_mfma_f32_16x16x32_bf16 v[122:125], v[184:187], v[208:211], v[122:125]
	v_mfma_f32_16x16x32_bf16 v[110:113], v[164:167], v[216:219], v[110:113]
	v_mfma_f32_16x16x32_bf16 v[106:109], v[184:187], v[216:219], v[106:109]
	v_mfma_f32_16x16x32_bf16 v[94:97], v[164:167], v[224:227], v[94:97]
	v_mfma_f32_16x16x32_bf16 v[90:93], v[184:187], v[224:227], v[90:93]
	v_mfma_f32_16x16x32_bf16 v[78:81], v[164:167], v[232:235], v[78:81]
	v_mfma_f32_16x16x32_bf16 v[74:77], v[184:187], v[232:235], v[74:77]
	v_mfma_f32_16x16x32_bf16 v[126:129], v[180:183], v[212:215], v[126:129]
	v_mfma_f32_16x16x32_bf16 v[122:125], v[188:191], v[212:215], v[122:125]
	v_mfma_f32_16x16x32_bf16 v[110:113], v[180:183], v[220:223], v[110:113]
	v_mfma_f32_16x16x32_bf16 v[106:109], v[188:191], v[220:223], v[106:109]
	v_mfma_f32_16x16x32_bf16 v[94:97], v[180:183], v[228:231], v[94:97]
	v_mfma_f32_16x16x32_bf16 v[90:93], v[188:191], v[228:231], v[90:93]
	v_mfma_f32_16x16x32_bf16 v[78:81], v[180:183], v[236:239], v[78:81]
	v_mfma_f32_16x16x32_bf16 v[74:77], v[188:191], v[236:239], v[74:77]
	s_setprio 0
	s_setprio 1
	v_mfma_f32_16x16x32_bf16 v[118:121], v[192:195], v[208:211], v[118:121]
	v_mfma_f32_16x16x32_bf16 v[114:117], v[200:203], v[208:211], v[114:117]
	v_mfma_f32_16x16x32_bf16 v[102:105], v[192:195], v[216:219], v[102:105]
	v_mfma_f32_16x16x32_bf16 v[98:101], v[200:203], v[216:219], v[98:101]
	v_mfma_f32_16x16x32_bf16 v[86:89], v[192:195], v[224:227], v[86:89]
	v_mfma_f32_16x16x32_bf16 v[82:85], v[200:203], v[224:227], v[82:85]
	v_mfma_f32_16x16x32_bf16 v[70:73], v[192:195], v[232:235], v[70:73]
	v_mfma_f32_16x16x32_bf16 v[66:69], v[200:203], v[232:235], v[66:69]
	v_mfma_f32_16x16x32_bf16 v[118:121], v[196:199], v[212:215], v[118:121]
	v_mfma_f32_16x16x32_bf16 v[114:117], v[204:207], v[212:215], v[114:117]
	v_mfma_f32_16x16x32_bf16 v[102:105], v[196:199], v[220:223], v[102:105]
	v_mfma_f32_16x16x32_bf16 v[98:101], v[204:207], v[220:223], v[98:101]
	v_mfma_f32_16x16x32_bf16 v[86:89], v[196:199], v[228:231], v[86:89]
	v_mfma_f32_16x16x32_bf16 v[82:85], v[204:207], v[228:231], v[82:85]
	v_mfma_f32_16x16x32_bf16 v[70:73], v[196:199], v[236:239], v[70:73]
	v_mfma_f32_16x16x32_bf16 v[66:69], v[204:207], v[236:239], v[66:69]
	s_setprio 0
	s_barrier
	s_add_i32 s62, s56, s45
	v_lshl_add_u64 v[176:177], s[38:39], 0, v[132:133]
	s_mov_b32 m0, s62
	ds_read_b128 v[208:211], v175 offset:16384
	ds_read_b128 v[212:215], v175 offset:17408
	ds_read_b128 v[216:219], v175 offset:18432
	ds_read_b128 v[220:223], v175 offset:19456
	ds_read_b128 v[224:227], v175 offset:20480
	ds_read_b128 v[228:231], v175 offset:21504
	ds_read_b128 v[232:235], v175 offset:22528
	ds_read_b128 v[236:239], v175 offset:23552
	global_load_lds_dwordx4 v[176:177], off
	s_add_i32 m0, s62, 0x2000
	s_add_u32 s62, s38, 0x40000
	v_lshl_add_u64 v[240:241], s[38:39], 0, v[136:137]
	s_addc_u32 s63, s39, 0
	s_add_i32 s64, s57, s45
	global_load_lds_dwordx4 v[240:241], off
	v_lshl_add_u64 v[242:243], s[62:63], 0, v[132:133]
	s_mov_b32 m0, s64
	v_lshl_add_u64 v[244:245], s[40:41], 0, v[134:135]
	global_load_lds_dwordx4 v[242:243], off
	v_lshl_add_u64 v[242:243], s[62:63], 0, v[136:137]
	s_add_i32 m0, s64, 0x2000
	s_nop 0
	global_load_lds_dwordx4 v[242:243], off
	v_lshl_add_u64 v[242:243], s[40:41], 0, v[130:131]
	s_mov_b32 m0, s35
	s_nop 0
	global_load_lds_dwordx4 v[242:243], off
	s_mov_b32 m0, s46
	s_nop 0
	global_load_lds_dwordx4 v[244:245], off
	s_waitcnt vmcnt(8)
	s_waitcnt lgkmcnt(0)
	s_barrier
	s_setprio 1
	s_waitcnt lgkmcnt(0)
	v_mfma_f32_16x16x32_bf16 v[62:65], v[164:167], v[208:211], v[62:65]
	v_mfma_f32_16x16x32_bf16 v[58:61], v[184:187], v[208:211], v[58:61]
	v_mfma_f32_16x16x32_bf16 v[46:49], v[164:167], v[216:219], v[46:49]
	v_mfma_f32_16x16x32_bf16 v[42:45], v[184:187], v[216:219], v[42:45]
	v_mfma_f32_16x16x32_bf16 v[30:33], v[164:167], v[224:227], v[30:33]
	v_mfma_f32_16x16x32_bf16 v[26:29], v[184:187], v[224:227], v[26:29]
	v_mfma_f32_16x16x32_bf16 v[14:17], v[164:167], v[232:235], v[14:17]
	v_mfma_f32_16x16x32_bf16 v[10:13], v[184:187], v[232:235], v[10:13]
	v_mfma_f32_16x16x32_bf16 v[62:65], v[180:183], v[212:215], v[62:65]
	v_mfma_f32_16x16x32_bf16 v[58:61], v[188:191], v[212:215], v[58:61]
	v_mfma_f32_16x16x32_bf16 v[46:49], v[180:183], v[220:223], v[46:49]
	v_mfma_f32_16x16x32_bf16 v[42:45], v[188:191], v[220:223], v[42:45]
	v_mfma_f32_16x16x32_bf16 v[30:33], v[180:183], v[228:231], v[30:33]
	v_mfma_f32_16x16x32_bf16 v[26:29], v[188:191], v[228:231], v[26:29]
	v_mfma_f32_16x16x32_bf16 v[14:17], v[180:183], v[236:239], v[14:17]
	v_mfma_f32_16x16x32_bf16 v[10:13], v[188:191], v[236:239], v[10:13]
	s_setprio 0
	s_setprio 1
	v_mfma_f32_16x16x32_bf16 v[54:57], v[192:195], v[208:211], v[54:57]
	v_mfma_f32_16x16x32_bf16 v[50:53], v[200:203], v[208:211], v[50:53]
	v_mfma_f32_16x16x32_bf16 v[38:41], v[192:195], v[216:219], v[38:41]
	v_mfma_f32_16x16x32_bf16 v[34:37], v[200:203], v[216:219], v[34:37]
	v_mfma_f32_16x16x32_bf16 v[22:25], v[192:195], v[224:227], v[22:25]
	v_mfma_f32_16x16x32_bf16 v[18:21], v[200:203], v[224:227], v[18:21]
	v_mfma_f32_16x16x32_bf16 v[6:9], v[192:195], v[232:235], v[6:9]
	v_mfma_f32_16x16x32_bf16 v[2:5], v[200:203], v[232:235], v[2:5]
	v_mfma_f32_16x16x32_bf16 v[54:57], v[196:199], v[212:215], v[54:57]
	v_mfma_f32_16x16x32_bf16 v[50:53], v[204:207], v[212:215], v[50:53]
	v_mfma_f32_16x16x32_bf16 v[38:41], v[196:199], v[220:223], v[38:41]
	v_mfma_f32_16x16x32_bf16 v[34:37], v[204:207], v[220:223], v[34:37]
	v_mfma_f32_16x16x32_bf16 v[22:25], v[196:199], v[228:231], v[22:25]
	v_mfma_f32_16x16x32_bf16 v[18:21], v[204:207], v[228:231], v[18:21]
	v_mfma_f32_16x16x32_bf16 v[6:9], v[196:199], v[236:239], v[6:9]
	v_mfma_f32_16x16x32_bf16 v[2:5], v[204:207], v[236:239], v[2:5]
	s_setprio 0
	s_barrier
	s_add_i32 s62, 0, 0x18000
	v_add_u32_e32 v149, s62, v171
	s_add_i32 s63, 0, 0x1c000
	ds_read_b128 v[164:167], v149
	ds_read_b128 v[180:183], v149 offset:1024
	ds_read_b128 v[184:187], v149 offset:2048
	ds_read_b128 v[188:191], v149 offset:3072
	v_add_u32_e32 v149, s63, v171
	ds_read_b128 v[192:195], v149
	ds_read_b128 v[196:199], v149 offset:1024
	ds_read_b128 v[200:203], v149 offset:2048
	ds_read_b128 v[204:207], v149 offset:3072
	s_add_u32 s40, s40, 0x40000
	s_addc_u32 s41, s41, 0
	s_mov_b32 m0, s47
	v_lshl_add_u64 v[246:247], s[40:41], 0, v[130:131]
	ds_read_b128 v[208:211], v175 offset:32768
	ds_read_b128 v[212:215], v175 offset:33792
	ds_read_b128 v[216:219], v175 offset:34816
	ds_read_b128 v[220:223], v175 offset:35840
	ds_read_b128 v[224:227], v175 offset:36864
	ds_read_b128 v[228:231], v175 offset:37888
	ds_read_b128 v[232:235], v175 offset:38912
	ds_read_b128 v[236:239], v175 offset:39936
	global_load_lds_dwordx4 v[246:247], off
	v_lshl_add_u64 v[246:247], s[40:41], 0, v[134:135]
	s_mov_b32 m0, s48
	s_nop 0
	global_load_lds_dwordx4 v[246:247], off
	s_waitcnt vmcnt(8)
	s_waitcnt lgkmcnt(0)
	s_barrier
	s_setprio 1
	s_waitcnt lgkmcnt(0)
	v_mfma_f32_16x16x32_bf16 v[126:129], v[164:167], v[208:211], v[126:129]
	v_mfma_f32_16x16x32_bf16 v[122:125], v[184:187], v[208:211], v[122:125]
	v_mfma_f32_16x16x32_bf16 v[110:113], v[164:167], v[216:219], v[110:113]
	v_mfma_f32_16x16x32_bf16 v[106:109], v[184:187], v[216:219], v[106:109]
	v_mfma_f32_16x16x32_bf16 v[94:97], v[164:167], v[224:227], v[94:97]
	v_mfma_f32_16x16x32_bf16 v[90:93], v[184:187], v[224:227], v[90:93]
	v_mfma_f32_16x16x32_bf16 v[78:81], v[164:167], v[232:235], v[78:81]
	v_mfma_f32_16x16x32_bf16 v[74:77], v[184:187], v[232:235], v[74:77]
	v_mfma_f32_16x16x32_bf16 v[126:129], v[180:183], v[212:215], v[126:129]
	v_mfma_f32_16x16x32_bf16 v[122:125], v[188:191], v[212:215], v[122:125]
	v_mfma_f32_16x16x32_bf16 v[110:113], v[180:183], v[220:223], v[110:113]
	v_mfma_f32_16x16x32_bf16 v[106:109], v[188:191], v[220:223], v[106:109]
	v_mfma_f32_16x16x32_bf16 v[94:97], v[180:183], v[228:231], v[94:97]
	v_mfma_f32_16x16x32_bf16 v[90:93], v[188:191], v[228:231], v[90:93]
	v_mfma_f32_16x16x32_bf16 v[78:81], v[180:183], v[236:239], v[78:81]
	v_mfma_f32_16x16x32_bf16 v[74:77], v[188:191], v[236:239], v[74:77]
	s_setprio 0
	s_setprio 1
	v_mfma_f32_16x16x32_bf16 v[118:121], v[192:195], v[208:211], v[118:121]
	v_mfma_f32_16x16x32_bf16 v[114:117], v[200:203], v[208:211], v[114:117]
	v_mfma_f32_16x16x32_bf16 v[102:105], v[192:195], v[216:219], v[102:105]
	v_mfma_f32_16x16x32_bf16 v[98:101], v[200:203], v[216:219], v[98:101]
	v_mfma_f32_16x16x32_bf16 v[86:89], v[192:195], v[224:227], v[86:89]
	v_mfma_f32_16x16x32_bf16 v[82:85], v[200:203], v[224:227], v[82:85]
	v_mfma_f32_16x16x32_bf16 v[70:73], v[192:195], v[232:235], v[70:73]
	v_mfma_f32_16x16x32_bf16 v[66:69], v[200:203], v[232:235], v[66:69]
	v_mfma_f32_16x16x32_bf16 v[118:121], v[196:199], v[212:215], v[118:121]
	v_mfma_f32_16x16x32_bf16 v[114:117], v[204:207], v[212:215], v[114:117]
	v_mfma_f32_16x16x32_bf16 v[102:105], v[196:199], v[220:223], v[102:105]
	v_mfma_f32_16x16x32_bf16 v[98:101], v[204:207], v[220:223], v[98:101]
	v_mfma_f32_16x16x32_bf16 v[86:89], v[196:199], v[228:231], v[86:89]
	v_mfma_f32_16x16x32_bf16 v[82:85], v[204:207], v[228:231], v[82:85]
	v_mfma_f32_16x16x32_bf16 v[70:73], v[196:199], v[236:239], v[70:73]
	v_mfma_f32_16x16x32_bf16 v[66:69], v[204:207], v[236:239], v[66:69]
	s_setprio 0
	s_barrier
	s_add_i32 s40, s62, s45
	v_lshl_add_u64 v[176:177], v[176:177], 0, s[8:9]
	s_mov_b32 m0, s40
	ds_read_b128 v[208:211], v175 offset:49152
	ds_read_b128 v[212:215], v175 offset:50176
	ds_read_b128 v[216:219], v175 offset:51200
	ds_read_b128 v[220:223], v175 offset:52224
	ds_read_b128 v[224:227], v175 offset:53248
	ds_read_b128 v[228:231], v175 offset:54272
	ds_read_b128 v[232:235], v175 offset:55296
	ds_read_b128 v[236:239], v175 offset:56320
	global_load_lds_dwordx4 v[176:177], off
	s_add_i32 m0, s40, 0x2000
	s_add_u32 s38, s38, 0x40080
	v_lshl_add_u64 v[176:177], v[240:241], 0, s[8:9]
	s_addc_u32 s39, s39, 0
	s_add_i32 s40, s63, s45
	global_load_lds_dwordx4 v[176:177], off
	v_lshl_add_u64 v[176:177], s[38:39], 0, v[132:133]
	s_mov_b32 m0, s40
	s_nop 0
	global_load_lds_dwordx4 v[176:177], off
	v_lshl_add_u64 v[176:177], s[38:39], 0, v[136:137]
	s_add_i32 m0, s40, 0x2000
	s_nop 0
	global_load_lds_dwordx4 v[176:177], off
	v_lshl_add_u64 v[176:177], v[242:243], 0, s[8:9]
	s_mov_b32 m0, s51
	s_nop 0
	global_load_lds_dwordx4 v[176:177], off
	v_lshl_add_u64 v[176:177], v[244:245], 0, s[8:9]
	s_mov_b32 m0, s52
	s_nop 0
	global_load_lds_dwordx4 v[176:177], off
	s_waitcnt vmcnt(8)
	s_waitcnt lgkmcnt(0)
	s_barrier
	s_setprio 1
	s_waitcnt lgkmcnt(0)
	v_mfma_f32_16x16x32_bf16 v[62:65], v[164:167], v[208:211], v[62:65]
	v_mfma_f32_16x16x32_bf16 v[58:61], v[184:187], v[208:211], v[58:61]
	v_mfma_f32_16x16x32_bf16 v[46:49], v[164:167], v[216:219], v[46:49]
	v_mfma_f32_16x16x32_bf16 v[42:45], v[184:187], v[216:219], v[42:45]
	v_mfma_f32_16x16x32_bf16 v[30:33], v[164:167], v[224:227], v[30:33]
	v_mfma_f32_16x16x32_bf16 v[26:29], v[184:187], v[224:227], v[26:29]
	v_mfma_f32_16x16x32_bf16 v[14:17], v[164:167], v[232:235], v[14:17]
	v_mfma_f32_16x16x32_bf16 v[10:13], v[184:187], v[232:235], v[10:13]
	v_mfma_f32_16x16x32_bf16 v[62:65], v[180:183], v[212:215], v[62:65]
	v_mfma_f32_16x16x32_bf16 v[58:61], v[188:191], v[212:215], v[58:61]
	v_mfma_f32_16x16x32_bf16 v[46:49], v[180:183], v[220:223], v[46:49]
	v_mfma_f32_16x16x32_bf16 v[42:45], v[188:191], v[220:223], v[42:45]
	v_mfma_f32_16x16x32_bf16 v[30:33], v[180:183], v[228:231], v[30:33]
	v_mfma_f32_16x16x32_bf16 v[26:29], v[188:191], v[228:231], v[26:29]
	v_mfma_f32_16x16x32_bf16 v[14:17], v[180:183], v[236:239], v[14:17]
	v_mfma_f32_16x16x32_bf16 v[10:13], v[188:191], v[236:239], v[10:13]
	s_setprio 0
	s_setprio 1
	v_mfma_f32_16x16x32_bf16 v[54:57], v[192:195], v[208:211], v[54:57]
	v_mfma_f32_16x16x32_bf16 v[50:53], v[200:203], v[208:211], v[50:53]
	v_mfma_f32_16x16x32_bf16 v[38:41], v[192:195], v[216:219], v[38:41]
	v_mfma_f32_16x16x32_bf16 v[34:37], v[200:203], v[216:219], v[34:37]
	v_mfma_f32_16x16x32_bf16 v[22:25], v[192:195], v[224:227], v[22:25]
	v_mfma_f32_16x16x32_bf16 v[18:21], v[200:203], v[224:227], v[18:21]
	v_mfma_f32_16x16x32_bf16 v[6:9], v[192:195], v[232:235], v[6:9]
	v_mfma_f32_16x16x32_bf16 v[2:5], v[200:203], v[232:235], v[2:5]
	v_mfma_f32_16x16x32_bf16 v[54:57], v[196:199], v[212:215], v[54:57]
	v_mfma_f32_16x16x32_bf16 v[50:53], v[204:207], v[212:215], v[50:53]
	v_mfma_f32_16x16x32_bf16 v[38:41], v[196:199], v[220:223], v[38:41]
	v_mfma_f32_16x16x32_bf16 v[34:37], v[204:207], v[220:223], v[34:37]
	v_mfma_f32_16x16x32_bf16 v[22:25], v[196:199], v[228:231], v[22:25]
	v_mfma_f32_16x16x32_bf16 v[18:21], v[204:207], v[228:231], v[18:21]
	v_mfma_f32_16x16x32_bf16 v[6:9], v[196:199], v[236:239], v[6:9]
	v_mfma_f32_16x16x32_bf16 v[2:5], v[204:207], v[236:239], v[2:5]
	s_setprio 0
	s_barrier
	s_add_i32 s61, s61, 2
	s_add_u32 s59, s59, 0x100
	s_addc_u32 s60, s60, 0
	s_add_u32 s36, s36, 0x100
	s_addc_u32 s37, s37, 0
	s_cmp_gt_u32 s61, 13
	s_cbranch_scc0 .LBB0_858
	s_andn2_b64 vcc, exec, s[2:3]
	s_cbranch_vccnz .Lrs8h_skip1
	v_lshl_add_u32 v188, s24, 8, v170
	v_ashrrev_i32_e32 v189, 31, v188
	v_lshlrev_b64 v[180:181], 6, v[188:189]
	v_lshl_add_u64 v[196:197], v[138:139], 0, v[180:181]
	v_or_b32_e32 v180, 16, v188
	v_or_b32_e32 v190, 32, v188
	v_or_b32_e32 v188, 48, v188
	v_ashrrev_i32_e32 v181, 31, v180
	v_ashrrev_i32_e32 v191, 31, v190
	v_ashrrev_i32_e32 v189, 31, v188
	v_lshlrev_b64 v[180:181], 6, v[180:181]
	v_lshlrev_b64 v[190:191], 6, v[190:191]
	v_lshlrev_b64 v[188:189], 6, v[188:189]
	v_add_co_u32_e32 v208, vcc, s49, v196
	v_lshl_add_u64 v[184:185], v[138:139], 0, v[180:181]
	v_lshl_add_u64 v[190:191], v[138:139], 0, v[190:191]
	v_lshl_add_u64 v[192:193], v[138:139], 0, v[188:189]
	v_addc_co_u32_e32 v209, vcc, 0, v197, vcc
	flat_load_dwordx4 v[180:183], v[196:197]
	s_nop 0
	flat_load_dwordx4 v[184:187], v[184:185]
	s_nop 0
	flat_load_dwordx4 v[188:191], v[190:191]
	s_nop 0
	flat_load_dwordx4 v[192:195], v[192:193]
	s_nop 0
	flat_load_dwordx4 v[196:199], v[208:209]
	flat_load_dwordx4 v[200:203], v[208:209] offset:1024
	flat_load_dwordx4 v[204:207], v[208:209] offset:2048
	s_nop 0
	flat_load_dwordx4 v[208:211], v[208:209] offset:3072
.Lrs8h_skip1:
	s_and_b64 vcc, exec, s[10:11]
	s_cbranch_vccz .LBB0_861
	s_barrier

.LBB0_925:
	s_andn2_b64 vcc, exec, s[2:3]
	s_mov_b64 s[2:3], -1
	s_cbranch_vccnz .LBB0_850
	s_andn2_b64 vcc, exec, s[0:1]
	s_waitcnt vmcnt(8) lgkmcnt(0)
	v_mov_b64_e32 v[2:3], v[180:181]
	v_mov_b64_e32 v[4:5], v[182:183]
	v_mov_b64_e32 v[6:7], v[184:185]
	v_mov_b64_e32 v[8:9], v[186:187]
	v_mov_b64_e32 v[10:11], v[188:189]
	v_mov_b64_e32 v[12:13], v[190:191]
	v_mov_b64_e32 v[14:15], v[192:193]
	v_mov_b64_e32 v[16:17], v[194:195]
	v_mov_b64_e32 v[18:19], v[196:197]
	v_mov_b64_e32 v[20:21], v[198:199]
	v_mov_b64_e32 v[22:23], v[200:201]
	v_mov_b64_e32 v[24:25], v[202:203]
	v_mov_b64_e32 v[26:27], v[204:205]
	v_mov_b64_e32 v[28:29], v[206:207]
	v_mov_b64_e32 v[30:31], v[208:209]
	v_mov_b64_e32 v[32:33], v[210:211]
	v_mov_b32_e32 v34, v3
	v_mov_b32_e32 v35, v4
	v_mov_b32_e32 v3, v5
	v_pk_add_f32 v[2:3], v[34:35], v[2:3]
	v_mov_b32_e32 v4, v7
	v_mov_b32_e32 v5, v8
	v_mov_b32_e32 v7, v9
	v_mov_b32_e32 v8, v11
	v_mov_b32_e32 v9, v12
	v_mov_b32_e32 v11, v13
	v_mov_b32_e32 v12, v15
	v_mov_b32_e32 v13, v16
	v_mov_b32_e32 v15, v17
	v_mov_b32_e32 v16, v19
	v_mov_b32_e32 v17, v20
	v_mov_b32_e32 v19, v21
	v_mov_b32_e32 v20, v23
	v_mov_b32_e32 v21, v24
	v_mov_b32_e32 v23, v25
	v_mov_b32_e32 v24, v27
	v_mov_b32_e32 v25, v28
	v_mov_b32_e32 v27, v29
	v_mov_b32_e32 v28, v31
	v_mov_b32_e32 v29, v32
	v_mov_b32_e32 v31, v33
	v_add_f32_e32 v32, v2, v3
	v_pk_add_f32 v[2:3], v[4:5], v[6:7]
	v_pk_add_f32 v[4:5], v[8:9], v[10:11]
	v_pk_add_f32 v[6:7], v[12:13], v[14:15]
	v_pk_add_f32 v[8:9], v[16:17], v[18:19]
	v_pk_add_f32 v[10:11], v[20:21], v[22:23]
	v_pk_add_f32 v[12:13], v[24:25], v[26:27]
	v_pk_add_f32 v[14:15], v[28:29], v[30:31]
	v_add_f32_e32 v2, v2, v3
	v_add_f32_e32 v3, v4, v5
	v_add_f32_e32 v4, v6, v7
	v_add_f32_e32 v5, v8, v9
	v_add_f32_e32 v6, v10, v11
	v_add_f32_e32 v8, v12, v13
	v_add_f32_e32 v10, v14, v15
	ds_bpermute_b32 v16, v1, v32
	ds_bpermute_b32 v7, v1, v2
	ds_bpermute_b32 v9, v1, v3
	ds_bpermute_b32 v13, v1, v4
	ds_bpermute_b32 v15, v1, v5
	ds_bpermute_b32 v17, v1, v6
	ds_bpermute_b32 v18, v1, v8
	ds_bpermute_b32 v19, v1, v10
	s_waitcnt lgkmcnt(7)
	v_add_f32_e32 v12, v32, v16
	s_waitcnt lgkmcnt(6)
	v_add_f32_e32 v11, v2, v7
	s_waitcnt lgkmcnt(5)
	v_add_f32_e32 v9, v3, v9
	s_waitcnt lgkmcnt(4)
	v_add_f32_e32 v7, v4, v13
	s_waitcnt lgkmcnt(3)
	v_add_f32_e32 v5, v5, v15
	s_waitcnt lgkmcnt(2)
	v_add_f32_e32 v4, v6, v17
	s_waitcnt lgkmcnt(1)
	v_add_f32_e32 v3, v8, v18
	s_waitcnt lgkmcnt(0)
	v_add_f32_e32 v2, v10, v19
	ds_bpermute_b32 v14, v168, v12
	ds_bpermute_b32 v17, v168, v11
	ds_bpermute_b32 v16, v168, v9
	ds_bpermute_b32 v15, v168, v7
	ds_bpermute_b32 v13, v168, v5
	ds_bpermute_b32 v10, v168, v4
	ds_bpermute_b32 v8, v168, v3
	ds_bpermute_b32 v6, v168, v2
	s_cbranch_vccnz .LBB0_849
	s_barrier
	s_branch .LBB0_849

.LBB0_1477:
	ds_read_b128 v[82:85], v180
	ds_read_b128 v[86:89], v180 offset:1024
	ds_read_b128 v[90:93], v180 offset:2048
	ds_read_b128 v[94:97], v180 offset:3072
	ds_read_b128 v[168:171], v181
	ds_read_b128 v[192:195], v181 offset:1024
	ds_read_b128 v[196:199], v181 offset:2048
	ds_read_b128 v[200:203], v181 offset:3072
	s_add_u32 s8, s6, 0xfffc0080
	s_addc_u32 s9, s7, -1
	s_cmp_eq_u32 s61, 12
	s_cselect_b32 s37, s25, s9
	s_cselect_b32 s36, s57, s8
	s_cselect_b32 s9, s23, s60
	s_cselect_b32 s8, s58, s59
	v_lshl_add_u64 v[172:173], s[6:7], 0, v[160:161]
	s_add_i32 m0, s31, 0xc000
	ds_read_b128 v[204:207], v182
	ds_read_b128 v[208:211], v182 offset:1024
	ds_read_b128 v[212:215], v182 offset:2048
	ds_read_b128 v[216:219], v182 offset:3072
	ds_read_b128 v[220:223], v182 offset:4096
	ds_read_b128 v[224:227], v182 offset:5120
	ds_read_b128 v[228:231], v182 offset:6144
	ds_read_b128 v[232:235], v182 offset:7168
	global_load_lds_dwordx4 v[172:173], off
	v_lshl_add_u64 v[172:173], s[6:7], 0, v[158:159]
	s_add_i32 m0, s31, 0xe000
	s_nop 0
	global_load_lds_dwordx4 v[172:173], off
	s_waitcnt vmcnt(8)
	s_waitcnt lgkmcnt(0)
	s_barrier
	s_setprio 1
	s_waitcnt lgkmcnt(0)
	v_mfma_f32_16x16x32_bf16 v[142:145], v[82:85], v[204:207], v[142:145]
	v_mfma_f32_16x16x32_bf16 v[138:141], v[90:93], v[204:207], v[138:141]
	v_mfma_f32_16x16x32_bf16 v[126:129], v[82:85], v[212:215], v[126:129]
	v_mfma_f32_16x16x32_bf16 v[122:125], v[90:93], v[212:215], v[122:125]
	v_mfma_f32_16x16x32_bf16 v[110:113], v[82:85], v[220:223], v[110:113]
	v_mfma_f32_16x16x32_bf16 v[106:109], v[90:93], v[220:223], v[106:109]
	v_mfma_f32_16x16x32_bf16 v[78:81], v[82:85], v[228:231], v[78:81]
	v_mfma_f32_16x16x32_bf16 v[74:77], v[90:93], v[228:231], v[74:77]
	v_mfma_f32_16x16x32_bf16 v[142:145], v[86:89], v[208:211], v[142:145]
	v_mfma_f32_16x16x32_bf16 v[138:141], v[94:97], v[208:211], v[138:141]
	v_mfma_f32_16x16x32_bf16 v[126:129], v[86:89], v[216:219], v[126:129]
	v_mfma_f32_16x16x32_bf16 v[122:125], v[94:97], v[216:219], v[122:125]
	v_mfma_f32_16x16x32_bf16 v[110:113], v[86:89], v[224:227], v[110:113]
	v_mfma_f32_16x16x32_bf16 v[106:109], v[94:97], v[224:227], v[106:109]
	v_mfma_f32_16x16x32_bf16 v[78:81], v[86:89], v[232:235], v[78:81]
	v_mfma_f32_16x16x32_bf16 v[74:77], v[94:97], v[232:235], v[74:77]
	s_setprio 0
	s_setprio 1
	v_mfma_f32_16x16x32_bf16 v[134:137], v[168:171], v[204:207], v[134:137]
	v_mfma_f32_16x16x32_bf16 v[130:133], v[196:199], v[204:207], v[130:133]
	v_mfma_f32_16x16x32_bf16 v[118:121], v[168:171], v[212:215], v[118:121]
	v_mfma_f32_16x16x32_bf16 v[114:117], v[196:199], v[212:215], v[114:117]
	v_mfma_f32_16x16x32_bf16 v[102:105], v[168:171], v[220:223], v[102:105]
	v_mfma_f32_16x16x32_bf16 v[98:101], v[196:199], v[220:223], v[98:101]
	v_mfma_f32_16x16x32_bf16 v[70:73], v[168:171], v[228:231], v[70:73]
	v_mfma_f32_16x16x32_bf16 v[66:69], v[196:199], v[228:231], v[66:69]
	v_mfma_f32_16x16x32_bf16 v[134:137], v[192:195], v[208:211], v[134:137]
	v_mfma_f32_16x16x32_bf16 v[130:133], v[200:203], v[208:211], v[130:133]
	v_mfma_f32_16x16x32_bf16 v[118:121], v[192:195], v[216:219], v[118:121]
	v_mfma_f32_16x16x32_bf16 v[114:117], v[200:203], v[216:219], v[114:117]
	v_mfma_f32_16x16x32_bf16 v[102:105], v[192:195], v[224:227], v[102:105]
	v_mfma_f32_16x16x32_bf16 v[98:101], v[200:203], v[224:227], v[98:101]
	v_mfma_f32_16x16x32_bf16 v[70:73], v[192:195], v[232:235], v[70:73]
	v_mfma_f32_16x16x32_bf16 v[66:69], v[200:203], v[232:235], v[66:69]
	s_setprio 0
	s_barrier
	s_add_i32 s62, s54, s41
	v_lshl_add_u64 v[172:173], s[8:9], 0, v[148:149]
	s_mov_b32 m0, s62
	ds_read_b128 v[204:207], v182 offset:16384
	ds_read_b128 v[208:211], v182 offset:17408
	ds_read_b128 v[212:215], v182 offset:18432
	ds_read_b128 v[216:219], v182 offset:19456
	ds_read_b128 v[220:223], v182 offset:20480
	ds_read_b128 v[224:227], v182 offset:21504
	ds_read_b128 v[228:231], v182 offset:22528
	ds_read_b128 v[232:235], v182 offset:23552
	global_load_lds_dwordx4 v[172:173], off
	s_add_i32 m0, s62, 0x2000
	s_add_u32 s62, s8, 0x40000
	v_lshl_add_u64 v[236:237], s[8:9], 0, v[152:153]
	s_addc_u32 s63, s9, 0
	s_add_i32 s64, s55, s41
	global_load_lds_dwordx4 v[236:237], off
	v_lshl_add_u64 v[238:239], s[62:63], 0, v[148:149]
	s_mov_b32 m0, s64
	v_lshl_add_u64 v[240:241], s[36:37], 0, v[150:151]
	global_load_lds_dwordx4 v[238:239], off
	v_lshl_add_u64 v[238:239], s[62:63], 0, v[152:153]
	s_add_i32 m0, s64, 0x2000
	s_nop 0
	global_load_lds_dwordx4 v[238:239], off
	v_lshl_add_u64 v[238:239], s[36:37], 0, v[146:147]
	s_mov_b32 m0, s31
	s_nop 0
	global_load_lds_dwordx4 v[238:239], off
	s_mov_b32 m0, s35
	s_nop 0
	global_load_lds_dwordx4 v[240:241], off
	s_waitcnt vmcnt(8)
	s_waitcnt lgkmcnt(0)
	s_barrier
	s_setprio 1
	s_waitcnt lgkmcnt(0)
	v_mfma_f32_16x16x32_bf16 v[62:65], v[82:85], v[204:207], v[62:65]
	v_mfma_f32_16x16x32_bf16 v[58:61], v[90:93], v[204:207], v[58:61]
	v_mfma_f32_16x16x32_bf16 v[46:49], v[82:85], v[212:215], v[46:49]
	v_mfma_f32_16x16x32_bf16 v[42:45], v[90:93], v[212:215], v[42:45]
	v_mfma_f32_16x16x32_bf16 v[30:33], v[82:85], v[220:223], v[30:33]
	v_mfma_f32_16x16x32_bf16 v[26:29], v[90:93], v[220:223], v[26:29]
	v_mfma_f32_16x16x32_bf16 v[14:17], v[82:85], v[228:231], v[14:17]
	v_mfma_f32_16x16x32_bf16 v[10:13], v[90:93], v[228:231], v[10:13]
	v_mfma_f32_16x16x32_bf16 v[62:65], v[86:89], v[208:211], v[62:65]
	v_mfma_f32_16x16x32_bf16 v[58:61], v[94:97], v[208:211], v[58:61]
	v_mfma_f32_16x16x32_bf16 v[46:49], v[86:89], v[216:219], v[46:49]
	v_mfma_f32_16x16x32_bf16 v[42:45], v[94:97], v[216:219], v[42:45]
	v_mfma_f32_16x16x32_bf16 v[30:33], v[86:89], v[224:227], v[30:33]
	v_mfma_f32_16x16x32_bf16 v[26:29], v[94:97], v[224:227], v[26:29]
	v_mfma_f32_16x16x32_bf16 v[14:17], v[86:89], v[232:235], v[14:17]
	v_mfma_f32_16x16x32_bf16 v[10:13], v[94:97], v[232:235], v[10:13]
	s_setprio 0
	s_setprio 1
	v_mfma_f32_16x16x32_bf16 v[54:57], v[168:171], v[204:207], v[54:57]
	v_mfma_f32_16x16x32_bf16 v[50:53], v[196:199], v[204:207], v[50:53]
	v_mfma_f32_16x16x32_bf16 v[38:41], v[168:171], v[212:215], v[38:41]
	v_mfma_f32_16x16x32_bf16 v[34:37], v[196:199], v[212:215], v[34:37]
	v_mfma_f32_16x16x32_bf16 v[22:25], v[168:171], v[220:223], v[22:25]
	v_mfma_f32_16x16x32_bf16 v[18:21], v[196:199], v[220:223], v[18:21]
	v_mfma_f32_16x16x32_bf16 v[6:9], v[168:171], v[228:231], v[6:9]
	v_mfma_f32_16x16x32_bf16 v[2:5], v[196:199], v[228:231], v[2:5]
	v_mfma_f32_16x16x32_bf16 v[54:57], v[192:195], v[208:211], v[54:57]
	v_mfma_f32_16x16x32_bf16 v[50:53], v[200:203], v[208:211], v[50:53]
	v_mfma_f32_16x16x32_bf16 v[38:41], v[192:195], v[216:219], v[38:41]
	v_mfma_f32_16x16x32_bf16 v[34:37], v[200:203], v[216:219], v[34:37]
	v_mfma_f32_16x16x32_bf16 v[22:25], v[192:195], v[224:227], v[22:25]
	v_mfma_f32_16x16x32_bf16 v[18:21], v[200:203], v[224:227], v[18:21]
	v_mfma_f32_16x16x32_bf16 v[6:9], v[192:195], v[232:235], v[6:9]
	v_mfma_f32_16x16x32_bf16 v[2:5], v[200:203], v[232:235], v[2:5]
	s_setprio 0
	s_barrier
	s_add_i32 s62, 0, 0x18000
	s_add_i32 s63, 0, 0x1c000
	v_add_u32_e32 v94, s62, v177
	v_add_u32_e32 v166, s63, v177
	ds_read_b128 v[82:85], v94
	ds_read_b128 v[86:89], v94 offset:1024
	ds_read_b128 v[90:93], v94 offset:2048
	ds_read_b128 v[94:97], v94 offset:3072
	ds_read_b128 v[168:171], v166
	ds_read_b128 v[192:195], v166 offset:1024
	ds_read_b128 v[196:199], v166 offset:2048
	ds_read_b128 v[200:203], v166 offset:3072
	s_add_u32 s36, s36, 0x40000
	s_addc_u32 s37, s37, 0
	s_mov_b32 m0, s42
	v_lshl_add_u64 v[242:243], s[36:37], 0, v[146:147]
	ds_read_b128 v[204:207], v182 offset:32768
	ds_read_b128 v[208:211], v182 offset:33792
	ds_read_b128 v[212:215], v182 offset:34816
	ds_read_b128 v[216:219], v182 offset:35840
	ds_read_b128 v[220:223], v182 offset:36864
	ds_read_b128 v[224:227], v182 offset:37888
	ds_read_b128 v[228:231], v182 offset:38912
	ds_read_b128 v[232:235], v182 offset:39936
	global_load_lds_dwordx4 v[242:243], off
	v_lshl_add_u64 v[242:243], s[36:37], 0, v[150:151]
	s_mov_b32 m0, s43
	s_nop 0
	global_load_lds_dwordx4 v[242:243], off
	s_waitcnt vmcnt(8)
	s_waitcnt lgkmcnt(0)
	s_barrier
	s_setprio 1
	s_waitcnt lgkmcnt(0)
	v_mfma_f32_16x16x32_bf16 v[142:145], v[82:85], v[204:207], v[142:145]
	v_mfma_f32_16x16x32_bf16 v[138:141], v[90:93], v[204:207], v[138:141]
	v_mfma_f32_16x16x32_bf16 v[126:129], v[82:85], v[212:215], v[126:129]
	v_mfma_f32_16x16x32_bf16 v[122:125], v[90:93], v[212:215], v[122:125]
	v_mfma_f32_16x16x32_bf16 v[110:113], v[82:85], v[220:223], v[110:113]
	v_mfma_f32_16x16x32_bf16 v[106:109], v[90:93], v[220:223], v[106:109]
	v_mfma_f32_16x16x32_bf16 v[78:81], v[82:85], v[228:231], v[78:81]
	v_mfma_f32_16x16x32_bf16 v[74:77], v[90:93], v[228:231], v[74:77]
	v_mfma_f32_16x16x32_bf16 v[142:145], v[86:89], v[208:211], v[142:145]
	v_mfma_f32_16x16x32_bf16 v[138:141], v[94:97], v[208:211], v[138:141]
	v_mfma_f32_16x16x32_bf16 v[126:129], v[86:89], v[216:219], v[126:129]
	v_mfma_f32_16x16x32_bf16 v[122:125], v[94:97], v[216:219], v[122:125]
	v_mfma_f32_16x16x32_bf16 v[110:113], v[86:89], v[224:227], v[110:113]
	v_mfma_f32_16x16x32_bf16 v[106:109], v[94:97], v[224:227], v[106:109]
	v_mfma_f32_16x16x32_bf16 v[78:81], v[86:89], v[232:235], v[78:81]
	v_mfma_f32_16x16x32_bf16 v[74:77], v[94:97], v[232:235], v[74:77]
	s_setprio 0
	s_setprio 1
	v_mfma_f32_16x16x32_bf16 v[134:137], v[168:171], v[204:207], v[134:137]
	v_mfma_f32_16x16x32_bf16 v[130:133], v[196:199], v[204:207], v[130:133]
	v_mfma_f32_16x16x32_bf16 v[118:121], v[168:171], v[212:215], v[118:121]
	v_mfma_f32_16x16x32_bf16 v[114:117], v[196:199], v[212:215], v[114:117]
	v_mfma_f32_16x16x32_bf16 v[102:105], v[168:171], v[220:223], v[102:105]
	v_mfma_f32_16x16x32_bf16 v[98:101], v[196:199], v[220:223], v[98:101]
	v_mfma_f32_16x16x32_bf16 v[70:73], v[168:171], v[228:231], v[70:73]
	v_mfma_f32_16x16x32_bf16 v[66:69], v[196:199], v[228:231], v[66:69]
	v_mfma_f32_16x16x32_bf16 v[134:137], v[192:195], v[208:211], v[134:137]
	v_mfma_f32_16x16x32_bf16 v[130:133], v[200:203], v[208:211], v[130:133]
	v_mfma_f32_16x16x32_bf16 v[118:121], v[192:195], v[216:219], v[118:121]
	v_mfma_f32_16x16x32_bf16 v[114:117], v[200:203], v[216:219], v[114:117]
	v_mfma_f32_16x16x32_bf16 v[102:105], v[192:195], v[224:227], v[102:105]
	v_mfma_f32_16x16x32_bf16 v[98:101], v[200:203], v[224:227], v[98:101]
	v_mfma_f32_16x16x32_bf16 v[70:73], v[192:195], v[232:235], v[70:73]
	v_mfma_f32_16x16x32_bf16 v[66:69], v[200:203], v[232:235], v[66:69]
	s_setprio 0
	s_barrier
	s_add_i32 s36, s62, s41
	v_lshl_add_u64 v[172:173], v[172:173], 0, s[12:13]
	s_mov_b32 m0, s36
	ds_read_b128 v[204:207], v182 offset:49152
	ds_read_b128 v[208:211], v182 offset:50176
	ds_read_b128 v[212:215], v182 offset:51200
	ds_read_b128 v[216:219], v182 offset:52224
	ds_read_b128 v[220:223], v182 offset:53248
	ds_read_b128 v[224:227], v182 offset:54272
	ds_read_b128 v[228:231], v182 offset:55296
	ds_read_b128 v[232:235], v182 offset:56320
	global_load_lds_dwordx4 v[172:173], off
	s_add_i32 m0, s36, 0x2000
	s_add_u32 s8, s8, 0x40080
	v_lshl_add_u64 v[172:173], v[236:237], 0, s[12:13]
	s_addc_u32 s9, s9, 0
	s_add_i32 s36, s63, s41
	global_load_lds_dwordx4 v[172:173], off
	v_lshl_add_u64 v[172:173], s[8:9], 0, v[148:149]
	s_mov_b32 m0, s36
	s_nop 0
	global_load_lds_dwordx4 v[172:173], off
	v_lshl_add_u64 v[172:173], s[8:9], 0, v[152:153]
	s_add_i32 m0, s36, 0x2000
	s_nop 0
	global_load_lds_dwordx4 v[172:173], off
	v_lshl_add_u64 v[172:173], v[238:239], 0, s[12:13]
	s_mov_b32 m0, s48
	s_nop 0
	global_load_lds_dwordx4 v[172:173], off
	v_lshl_add_u64 v[172:173], v[240:241], 0, s[12:13]
	s_mov_b32 m0, s49
	s_nop 0
	global_load_lds_dwordx4 v[172:173], off
	s_waitcnt vmcnt(8)
	s_waitcnt lgkmcnt(0)
	s_barrier
	s_setprio 1
	s_waitcnt lgkmcnt(0)
	v_mfma_f32_16x16x32_bf16 v[62:65], v[82:85], v[204:207], v[62:65]
	v_mfma_f32_16x16x32_bf16 v[58:61], v[90:93], v[204:207], v[58:61]
	v_mfma_f32_16x16x32_bf16 v[46:49], v[82:85], v[212:215], v[46:49]
	v_mfma_f32_16x16x32_bf16 v[42:45], v[90:93], v[212:215], v[42:45]
	v_mfma_f32_16x16x32_bf16 v[30:33], v[82:85], v[220:223], v[30:33]
	v_mfma_f32_16x16x32_bf16 v[26:29], v[90:93], v[220:223], v[26:29]
	v_mfma_f32_16x16x32_bf16 v[14:17], v[82:85], v[228:231], v[14:17]
	v_mfma_f32_16x16x32_bf16 v[10:13], v[90:93], v[228:231], v[10:13]
	v_mfma_f32_16x16x32_bf16 v[62:65], v[86:89], v[208:211], v[62:65]
	v_mfma_f32_16x16x32_bf16 v[58:61], v[94:97], v[208:211], v[58:61]
	v_mfma_f32_16x16x32_bf16 v[46:49], v[86:89], v[216:219], v[46:49]
	v_mfma_f32_16x16x32_bf16 v[42:45], v[94:97], v[216:219], v[42:45]
	v_mfma_f32_16x16x32_bf16 v[30:33], v[86:89], v[224:227], v[30:33]
	v_mfma_f32_16x16x32_bf16 v[26:29], v[94:97], v[224:227], v[26:29]
	v_mfma_f32_16x16x32_bf16 v[14:17], v[86:89], v[232:235], v[14:17]
	v_mfma_f32_16x16x32_bf16 v[10:13], v[94:97], v[232:235], v[10:13]
	s_setprio 0
	s_setprio 1
	v_mfma_f32_16x16x32_bf16 v[54:57], v[168:171], v[204:207], v[54:57]
	v_mfma_f32_16x16x32_bf16 v[50:53], v[196:199], v[204:207], v[50:53]
	v_mfma_f32_16x16x32_bf16 v[38:41], v[168:171], v[212:215], v[38:41]
	v_mfma_f32_16x16x32_bf16 v[34:37], v[196:199], v[212:215], v[34:37]
	v_mfma_f32_16x16x32_bf16 v[22:25], v[168:171], v[220:223], v[22:25]
	v_mfma_f32_16x16x32_bf16 v[18:21], v[196:199], v[220:223], v[18:21]
	v_mfma_f32_16x16x32_bf16 v[6:9], v[168:171], v[228:231], v[6:9]
	v_mfma_f32_16x16x32_bf16 v[2:5], v[196:199], v[228:231], v[2:5]
	v_mfma_f32_16x16x32_bf16 v[54:57], v[192:195], v[208:211], v[54:57]
	v_mfma_f32_16x16x32_bf16 v[50:53], v[200:203], v[208:211], v[50:53]
	v_mfma_f32_16x16x32_bf16 v[38:41], v[192:195], v[216:219], v[38:41]
	v_mfma_f32_16x16x32_bf16 v[34:37], v[200:203], v[216:219], v[34:37]
	v_mfma_f32_16x16x32_bf16 v[22:25], v[192:195], v[224:227], v[22:25]
	v_mfma_f32_16x16x32_bf16 v[18:21], v[200:203], v[224:227], v[18:21]
	v_mfma_f32_16x16x32_bf16 v[6:9], v[192:195], v[232:235], v[6:9]
	v_mfma_f32_16x16x32_bf16 v[2:5], v[200:203], v[232:235], v[2:5]
	s_setprio 0
	s_barrier
	s_add_i32 s61, s61, 2
	s_add_u32 s59, s59, 0x100
	s_addc_u32 s60, s60, 0
	s_add_u32 s6, s6, 0x100
	s_addc_u32 s7, s7, 0
	s_cmp_gt_u32 s61, 13
	s_cbranch_scc0 .LBB0_1477
	s_andn2_b64 vcc, exec, s[2:3]
	s_cbranch_vccnz .Lrs8h_skip2
	v_lshl_add_u32 v204, s24, 8, v176
	v_ashrrev_i32_e32 v205, 31, v204
	v_lshlrev_b64 v[196:197], 6, v[204:205]
	v_lshl_add_u64 v[212:213], v[156:157], 0, v[196:197]
	v_or_b32_e32 v196, 16, v204
	v_or_b32_e32 v206, 32, v204
	v_or_b32_e32 v204, 48, v204
	v_ashrrev_i32_e32 v197, 31, v196
	v_ashrrev_i32_e32 v207, 31, v206
	v_ashrrev_i32_e32 v205, 31, v204
	v_lshlrev_b64 v[196:197], 6, v[196:197]
	v_lshlrev_b64 v[206:207], 6, v[206:207]
	v_lshlrev_b64 v[204:205], 6, v[204:205]
	v_add_co_u32_e32 v224, vcc, s44, v212
	v_lshl_add_u64 v[200:201], v[156:157], 0, v[196:197]
	v_lshl_add_u64 v[206:207], v[156:157], 0, v[206:207]
	v_lshl_add_u64 v[208:209], v[156:157], 0, v[204:205]
	v_addc_co_u32_e32 v225, vcc, 0, v213, vcc
	flat_load_dwordx4 v[196:199], v[212:213]
	s_nop 0
	flat_load_dwordx4 v[200:203], v[200:201]
	s_nop 0
	flat_load_dwordx4 v[204:207], v[206:207]
	s_nop 0
	flat_load_dwordx4 v[208:211], v[208:209]
	s_nop 0
	flat_load_dwordx4 v[212:215], v[224:225]
	flat_load_dwordx4 v[216:219], v[224:225] offset:1024
	flat_load_dwordx4 v[220:223], v[224:225] offset:2048
	s_nop 0
	flat_load_dwordx4 v[224:227], v[224:225] offset:3072
.Lrs8h_skip2:
	s_and_b64 vcc, exec, s[14:15]
	s_cbranch_vccz .LBB0_1480
	s_barrier

.LBB0_1549:
	s_andn2_b64 vcc, exec, s[2:3]
	s_mov_b64 s[2:3], -1
	s_cbranch_vccnz .LBB0_1473
	s_andn2_b64 vcc, exec, s[10:11]
	s_waitcnt vmcnt(8) lgkmcnt(0)
	v_mov_b64_e32 v[2:3], v[196:197]
	v_mov_b64_e32 v[4:5], v[198:199]
	v_mov_b64_e32 v[6:7], v[200:201]
	v_mov_b64_e32 v[8:9], v[202:203]
	v_mov_b64_e32 v[10:11], v[204:205]
	v_mov_b64_e32 v[12:13], v[206:207]
	v_mov_b64_e32 v[14:15], v[208:209]
	v_mov_b64_e32 v[16:17], v[210:211]
	v_mov_b64_e32 v[18:19], v[212:213]
	v_mov_b64_e32 v[20:21], v[214:215]
	v_mov_b64_e32 v[22:23], v[216:217]
	v_mov_b64_e32 v[24:25], v[218:219]
	v_mov_b64_e32 v[26:27], v[220:221]
	v_mov_b64_e32 v[28:29], v[222:223]
	v_mov_b64_e32 v[30:31], v[224:225]
	v_mov_b64_e32 v[32:33], v[226:227]
	v_mov_b32_e32 v34, v3
	v_mov_b32_e32 v35, v4
	v_mov_b32_e32 v3, v5
	v_pk_add_f32 v[2:3], v[34:35], v[2:3]
	v_mov_b32_e32 v4, v7
	v_mov_b32_e32 v5, v8
	v_mov_b32_e32 v7, v9
	v_mov_b32_e32 v8, v11
	v_mov_b32_e32 v9, v12
	v_mov_b32_e32 v11, v13
	v_mov_b32_e32 v12, v15
	v_mov_b32_e32 v13, v16
	v_mov_b32_e32 v15, v17
	v_mov_b32_e32 v16, v19
	v_mov_b32_e32 v17, v20
	v_mov_b32_e32 v19, v21
	v_mov_b32_e32 v20, v23
	v_mov_b32_e32 v21, v24
	v_mov_b32_e32 v23, v25
	v_mov_b32_e32 v24, v27
	v_mov_b32_e32 v25, v28
	v_mov_b32_e32 v27, v29
	v_mov_b32_e32 v28, v31
	v_mov_b32_e32 v29, v32
	v_mov_b32_e32 v31, v33
	v_add_f32_e32 v32, v2, v3
	v_pk_add_f32 v[2:3], v[4:5], v[6:7]
	v_pk_add_f32 v[4:5], v[8:9], v[10:11]
	v_pk_add_f32 v[6:7], v[12:13], v[14:15]
	v_pk_add_f32 v[8:9], v[16:17], v[18:19]
	v_pk_add_f32 v[10:11], v[20:21], v[22:23]
	v_pk_add_f32 v[12:13], v[24:25], v[26:27]
	v_pk_add_f32 v[14:15], v[28:29], v[30:31]
	v_add_f32_e32 v2, v2, v3
	v_add_f32_e32 v3, v4, v5
	v_add_f32_e32 v4, v6, v7
	v_add_f32_e32 v5, v8, v9
	v_add_f32_e32 v6, v10, v11
	v_add_f32_e32 v8, v12, v13
	v_add_f32_e32 v10, v14, v15
	ds_bpermute_b32 v16, v1, v32
	ds_bpermute_b32 v7, v1, v2
	ds_bpermute_b32 v9, v1, v3
	ds_bpermute_b32 v13, v1, v4
	ds_bpermute_b32 v15, v1, v5
	ds_bpermute_b32 v17, v1, v6
	ds_bpermute_b32 v18, v1, v8
	ds_bpermute_b32 v19, v1, v10
	s_waitcnt lgkmcnt(7)
	v_add_f32_e32 v12, v32, v16
	s_waitcnt lgkmcnt(6)
	v_add_f32_e32 v11, v2, v7
	s_waitcnt lgkmcnt(5)
	v_add_f32_e32 v9, v3, v9
	s_waitcnt lgkmcnt(4)
	v_add_f32_e32 v7, v4, v13
	s_waitcnt lgkmcnt(3)
	v_add_f32_e32 v5, v5, v15
	s_waitcnt lgkmcnt(2)
	v_add_f32_e32 v4, v6, v17
	s_waitcnt lgkmcnt(1)
	v_add_f32_e32 v3, v8, v18
	s_waitcnt lgkmcnt(0)
	v_add_f32_e32 v2, v10, v19
	ds_bpermute_b32 v14, v174, v12
	ds_bpermute_b32 v17, v174, v11
	ds_bpermute_b32 v16, v174, v9
	ds_bpermute_b32 v15, v174, v7
	ds_bpermute_b32 v13, v174, v5
	ds_bpermute_b32 v10, v174, v4
	ds_bpermute_b32 v8, v174, v3
	ds_bpermute_b32 v6, v174, v2
	s_cbranch_vccnz .LBB0_1472
	s_barrier
	s_branch .LBB0_1472
